# per-unit accumulator clear in all gemm_phase loops: 64 v_pk_mov_b32 (two registers each) instead of 127 v_mov_b32
# baseline (speedup 1.0000x reference)
; template <class Epi, class Sched, bool ALIGN_EPI = false, bool SP2 = false>
; __device__ __forceinline__ void gemm_phase(PG8_LAS unsigned char* lds, const Gemm g, const Sched& S, const Epi& E) {
;     ...
;         const bool has_next = S.next(ui + 1, nxt);
;         const char* nA = has_next ? (const char*)g.A + (size_t)nxt.pm * tstep : cA; const char* nB = has_next ? (const char*)g.Bt + (size_t)nxt.pn * tstep : cB;
;     ...
;         for (int a = 0; a < 2; ++a)
; #pragma unroll
;             for (int b = 0; b < 2; ++b)
; #pragma unroll
;                 for (int m = 0; m < 4; ++m)
; #pragma unroll
;                     for (int n = 0; n < 2; ++n) acc[a][b][m][n] = (f32x4){0.f, 0.f, 0.f, 0.f};
.LBB0_233:
	s_ashr_i32 s45, s44, 31
	s_lshl_b64 s[52:53], s[44:45], 19
	s_add_u32 s52, s30, s52
	s_addc_u32 s53, s31, s53
	s_and_b64 s[54:55], s[0:1], exec
	s_cselect_b32 s45, s53, s11
	s_cselect_b32 s81, s52, s10
	s_ashr_i32 s35, s34, 31
	s_lshl_b64 s[54:55], s[34:35], 19
	s_add_u32 s54, s38, s54
	s_addc_u32 s55, s39, s55
	s_and_b64 s[58:59], s[0:1], exec
	s_cselect_b32 s35, s55, s7
	s_cselect_b32 s82, s54, s6
	s_add_u32 s58, s10, 0x40080
	s_addc_u32 s59, s11, 0
	s_add_u32 s83, s6, 0x100
	v_mov_b32_e32 v0, 0
	s_addc_u32 s84, s7, 0
	s_mov_b32 s85, -2
	v_mov_b32_e32 v1, 0
	v_pk_mov_b32 v[2:3], v[0:1], v[0:1]
	v_pk_mov_b32 v[4:5], v[0:1], v[0:1]
	v_pk_mov_b32 v[6:7], v[0:1], v[0:1]
	v_pk_mov_b32 v[8:9], v[0:1], v[0:1]
	v_pk_mov_b32 v[10:11], v[0:1], v[0:1]
	v_pk_mov_b32 v[12:13], v[0:1], v[0:1]
	v_pk_mov_b32 v[14:15], v[0:1], v[0:1]
	v_pk_mov_b32 v[16:17], v[0:1], v[0:1]
	v_pk_mov_b32 v[18:19], v[0:1], v[0:1]
	v_pk_mov_b32 v[20:21], v[0:1], v[0:1]
	v_pk_mov_b32 v[22:23], v[0:1], v[0:1]
	v_pk_mov_b32 v[24:25], v[0:1], v[0:1]
	v_pk_mov_b32 v[26:27], v[0:1], v[0:1]
	v_pk_mov_b32 v[28:29], v[0:1], v[0:1]
	v_pk_mov_b32 v[30:31], v[0:1], v[0:1]
	v_pk_mov_b32 v[32:33], v[0:1], v[0:1]
	v_pk_mov_b32 v[34:35], v[0:1], v[0:1]
	v_pk_mov_b32 v[36:37], v[0:1], v[0:1]
	v_pk_mov_b32 v[38:39], v[0:1], v[0:1]
	v_pk_mov_b32 v[40:41], v[0:1], v[0:1]
	v_pk_mov_b32 v[42:43], v[0:1], v[0:1]
	v_pk_mov_b32 v[44:45], v[0:1], v[0:1]
	v_pk_mov_b32 v[46:47], v[0:1], v[0:1]
	v_pk_mov_b32 v[48:49], v[0:1], v[0:1]
	v_pk_mov_b32 v[50:51], v[0:1], v[0:1]
	v_pk_mov_b32 v[52:53], v[0:1], v[0:1]
	v_pk_mov_b32 v[54:55], v[0:1], v[0:1]
	v_pk_mov_b32 v[56:57], v[0:1], v[0:1]
	v_pk_mov_b32 v[58:59], v[0:1], v[0:1]
	v_pk_mov_b32 v[60:61], v[0:1], v[0:1]
	v_pk_mov_b32 v[62:63], v[0:1], v[0:1]
	v_pk_mov_b32 v[64:65], v[0:1], v[0:1]
	v_pk_mov_b32 v[66:67], v[0:1], v[0:1]
	v_pk_mov_b32 v[68:69], v[0:1], v[0:1]
	v_pk_mov_b32 v[70:71], v[0:1], v[0:1]
	v_pk_mov_b32 v[72:73], v[0:1], v[0:1]
	v_pk_mov_b32 v[74:75], v[0:1], v[0:1]
	v_pk_mov_b32 v[76:77], v[0:1], v[0:1]
	v_pk_mov_b32 v[78:79], v[0:1], v[0:1]
	v_pk_mov_b32 v[80:81], v[0:1], v[0:1]
	v_pk_mov_b32 v[82:83], v[0:1], v[0:1]
	v_pk_mov_b32 v[84:85], v[0:1], v[0:1]
	v_pk_mov_b32 v[86:87], v[0:1], v[0:1]
	v_pk_mov_b32 v[88:89], v[0:1], v[0:1]
	v_pk_mov_b32 v[90:91], v[0:1], v[0:1]
	v_pk_mov_b32 v[92:93], v[0:1], v[0:1]
	v_pk_mov_b32 v[94:95], v[0:1], v[0:1]
	v_pk_mov_b32 v[96:97], v[0:1], v[0:1]
	v_pk_mov_b32 v[98:99], v[0:1], v[0:1]
	v_pk_mov_b32 v[100:101], v[0:1], v[0:1]
	v_pk_mov_b32 v[102:103], v[0:1], v[0:1]
	v_pk_mov_b32 v[104:105], v[0:1], v[0:1]
	v_pk_mov_b32 v[106:107], v[0:1], v[0:1]
	v_pk_mov_b32 v[108:109], v[0:1], v[0:1]
	v_pk_mov_b32 v[110:111], v[0:1], v[0:1]
	v_pk_mov_b32 v[112:113], v[0:1], v[0:1]
	v_pk_mov_b32 v[114:115], v[0:1], v[0:1]
	v_pk_mov_b32 v[116:117], v[0:1], v[0:1]
	v_pk_mov_b32 v[118:119], v[0:1], v[0:1]
	v_pk_mov_b32 v[120:121], v[0:1], v[0:1]
	v_pk_mov_b32 v[122:123], v[0:1], v[0:1]
	v_pk_mov_b32 v[124:125], v[0:1], v[0:1]
	v_pk_mov_b32 v[126:127], v[0:1], v[0:1]

; template <class Epi, class Sched, bool ALIGN_EPI = false, bool SP2 = false>
; __device__ __forceinline__ void gemm_phase(PG8_LAS unsigned char* lds, const Gemm g, const Sched& S, const Epi& E) {
;     ...
;         const bool has_next = S.next(ui + 1, nxt);
;         const char* nA = has_next ? (const char*)g.A + (size_t)nxt.pm * tstep : cA; const char* nB = has_next ? (const char*)g.Bt + (size_t)nxt.pn * tstep : cB;
;     ...
;         for (int a = 0; a < 2; ++a)
; #pragma unroll
;             for (int b = 0; b < 2; ++b)
; #pragma unroll
;                 for (int m = 0; m < 4; ++m)
; #pragma unroll
;                     for (int n = 0; n < 2; ++n) acc[a][b][m][n] = (f32x4){0.f, 0.f, 0.f, 0.f};
.LBB0_479:
	s_ashr_i32 s47, s46, 31
	s_lshl_b64 s[10:11], s[46:47], 9
	s_add_u32 s48, s70, s10
	s_addc_u32 s49, s71, s11
	s_add_u32 s48, s48, 0x18000000
	s_addc_u32 s49, s49, 0
	s_and_b64 s[10:11], s[4:5], exec
	s_cselect_b32 s47, s49, s9
	s_cselect_b32 s65, s48, s8
	s_ashr_i32 s35, s34, 31
	s_lshl_b64 s[10:11], s[34:35], 19
	s_add_u32 s50, s28, s10
	s_addc_u32 s51, s29, s11
	s_and_b64 s[10:11], s[4:5], exec
	s_cselect_b32 s35, s51, s7
	s_cselect_b32 s66, s50, s6
	s_add_u32 s8, s8, 0x400100
	s_addc_u32 s9, s9, 0
	s_add_u32 s67, s6, 0x100
	v_mov_b32_e32 v0, 0
	s_addc_u32 s76, s7, 0
	s_mov_b32 s77, -2
	s_waitcnt lgkmcnt(0)
	v_mov_b32_e32 v1, 0
	v_pk_mov_b32 v[2:3], v[0:1], v[0:1]
	v_pk_mov_b32 v[4:5], v[0:1], v[0:1]
	v_pk_mov_b32 v[6:7], v[0:1], v[0:1]
	v_pk_mov_b32 v[8:9], v[0:1], v[0:1]
	v_pk_mov_b32 v[10:11], v[0:1], v[0:1]
	v_pk_mov_b32 v[12:13], v[0:1], v[0:1]
	v_pk_mov_b32 v[14:15], v[0:1], v[0:1]
	v_pk_mov_b32 v[16:17], v[0:1], v[0:1]
	v_pk_mov_b32 v[18:19], v[0:1], v[0:1]
	v_pk_mov_b32 v[20:21], v[0:1], v[0:1]
	v_pk_mov_b32 v[22:23], v[0:1], v[0:1]
	v_pk_mov_b32 v[24:25], v[0:1], v[0:1]
	v_pk_mov_b32 v[26:27], v[0:1], v[0:1]
	v_pk_mov_b32 v[28:29], v[0:1], v[0:1]
	v_pk_mov_b32 v[30:31], v[0:1], v[0:1]
	v_pk_mov_b32 v[32:33], v[0:1], v[0:1]
	v_pk_mov_b32 v[34:35], v[0:1], v[0:1]
	v_pk_mov_b32 v[36:37], v[0:1], v[0:1]
	v_pk_mov_b32 v[38:39], v[0:1], v[0:1]
	v_pk_mov_b32 v[40:41], v[0:1], v[0:1]
	v_pk_mov_b32 v[42:43], v[0:1], v[0:1]
	v_pk_mov_b32 v[44:45], v[0:1], v[0:1]
	v_pk_mov_b32 v[46:47], v[0:1], v[0:1]
	v_pk_mov_b32 v[48:49], v[0:1], v[0:1]
	v_pk_mov_b32 v[50:51], v[0:1], v[0:1]
	v_pk_mov_b32 v[52:53], v[0:1], v[0:1]
	v_pk_mov_b32 v[54:55], v[0:1], v[0:1]
	v_pk_mov_b32 v[56:57], v[0:1], v[0:1]
	v_pk_mov_b32 v[58:59], v[0:1], v[0:1]
	v_pk_mov_b32 v[60:61], v[0:1], v[0:1]
	v_pk_mov_b32 v[62:63], v[0:1], v[0:1]
	v_pk_mov_b32 v[64:65], v[0:1], v[0:1]
	v_pk_mov_b32 v[66:67], v[0:1], v[0:1]
	v_pk_mov_b32 v[68:69], v[0:1], v[0:1]
	v_pk_mov_b32 v[70:71], v[0:1], v[0:1]
	v_pk_mov_b32 v[72:73], v[0:1], v[0:1]
	v_pk_mov_b32 v[74:75], v[0:1], v[0:1]
	v_pk_mov_b32 v[76:77], v[0:1], v[0:1]
	v_pk_mov_b32 v[78:79], v[0:1], v[0:1]
	v_pk_mov_b32 v[80:81], v[0:1], v[0:1]
	v_pk_mov_b32 v[82:83], v[0:1], v[0:1]
	v_pk_mov_b32 v[84:85], v[0:1], v[0:1]
	v_pk_mov_b32 v[86:87], v[0:1], v[0:1]
	v_pk_mov_b32 v[100:101], v[0:1], v[0:1]
	v_pk_mov_b32 v[102:103], v[0:1], v[0:1]
	v_pk_mov_b32 v[108:109], v[0:1], v[0:1]
	v_pk_mov_b32 v[110:111], v[0:1], v[0:1]
	v_pk_mov_b32 v[112:113], v[0:1], v[0:1]
	v_pk_mov_b32 v[114:115], v[0:1], v[0:1]
	v_pk_mov_b32 v[116:117], v[0:1], v[0:1]
	v_pk_mov_b32 v[118:119], v[0:1], v[0:1]
	v_pk_mov_b32 v[120:121], v[0:1], v[0:1]
	v_pk_mov_b32 v[122:123], v[0:1], v[0:1]
	v_pk_mov_b32 v[124:125], v[0:1], v[0:1]
	v_pk_mov_b32 v[126:127], v[0:1], v[0:1]
	v_pk_mov_b32 v[128:129], v[0:1], v[0:1]
	v_pk_mov_b32 v[130:131], v[0:1], v[0:1]
	v_pk_mov_b32 v[132:133], v[0:1], v[0:1]
	v_pk_mov_b32 v[134:135], v[0:1], v[0:1]
	v_pk_mov_b32 v[136:137], v[0:1], v[0:1]
	v_pk_mov_b32 v[138:139], v[0:1], v[0:1]
	v_pk_mov_b32 v[140:141], v[0:1], v[0:1]
	v_pk_mov_b32 v[142:143], v[0:1], v[0:1]

; template <class Epi, class Sched, bool ALIGN_EPI = false, bool SP2 = false>
; __device__ __forceinline__ void gemm_phase(PG8_LAS unsigned char* lds, const Gemm g, const Sched& S, const Epi& E) {
;     ...
;         const bool has_next = S.next(ui + 1, nxt);
;         const char* nA = has_next ? (const char*)g.A + (size_t)nxt.pm * tstep : cA; const char* nB = has_next ? (const char*)g.Bt + (size_t)nxt.pn * tstep : cB;
;     ...
;         for (int a = 0; a < 2; ++a)
; #pragma unroll
;             for (int b = 0; b < 2; ++b)
; #pragma unroll
;                 for (int m = 0; m < 4; ++m)
; #pragma unroll
;                     for (int n = 0; n < 2; ++n) acc[a][b][m][n] = (f32x4){0.f, 0.f, 0.f, 0.f};
.LBB0_574:
	s_ashr_i32 s19, s18, 31
	s_lshl_b64 s[20:21], s[18:19], 19
	s_add_u32 s20, s38, s20
	s_addc_u32 s21, s39, s21
	s_and_b64 s[26:27], s[0:1], exec
	s_cselect_b32 s19, s21, s11
	s_cselect_b32 s57, s20, s10
	s_ashr_i32 s17, s16, 31
	s_lshl_b64 s[26:27], s[16:17], 19
	s_add_u32 s26, s3, s26
	s_addc_u32 s27, s33, s27
	s_and_b64 s[30:31], s[0:1], exec
	s_cselect_b32 s17, s27, s7
	s_cselect_b32 s58, s26, s6
	s_add_u32 s30, s10, 0x40080
	s_addc_u32 s31, s11, 0
	s_add_u32 s59, s6, 0x100
	v_mov_b32_e32 v8, 0
	s_addc_u32 s60, s7, 0
	s_mov_b32 s61, -2
	v_mov_b32_e32 v9, 0
	v_pk_mov_b32 v[0:1], v[8:9], v[8:9]
	v_pk_mov_b32 v[2:3], v[8:9], v[8:9]
	v_pk_mov_b32 v[4:5], v[8:9], v[8:9]
	v_pk_mov_b32 v[6:7], v[8:9], v[8:9]
	v_pk_mov_b32 v[10:11], v[8:9], v[8:9]
	v_pk_mov_b32 v[12:13], v[8:9], v[8:9]
	v_pk_mov_b32 v[14:15], v[8:9], v[8:9]
	v_pk_mov_b32 v[16:17], v[8:9], v[8:9]
	v_pk_mov_b32 v[18:19], v[8:9], v[8:9]
	v_pk_mov_b32 v[20:21], v[8:9], v[8:9]
	v_pk_mov_b32 v[22:23], v[8:9], v[8:9]
	v_pk_mov_b32 v[24:25], v[8:9], v[8:9]
	v_pk_mov_b32 v[26:27], v[8:9], v[8:9]
	v_pk_mov_b32 v[28:29], v[8:9], v[8:9]
	v_pk_mov_b32 v[30:31], v[8:9], v[8:9]
	v_pk_mov_b32 v[32:33], v[8:9], v[8:9]
	v_pk_mov_b32 v[34:35], v[8:9], v[8:9]
	v_pk_mov_b32 v[36:37], v[8:9], v[8:9]
	v_pk_mov_b32 v[38:39], v[8:9], v[8:9]
	v_pk_mov_b32 v[40:41], v[8:9], v[8:9]
	v_pk_mov_b32 v[42:43], v[8:9], v[8:9]
	v_pk_mov_b32 v[44:45], v[8:9], v[8:9]
	v_pk_mov_b32 v[46:47], v[8:9], v[8:9]
	v_pk_mov_b32 v[48:49], v[8:9], v[8:9]
	v_pk_mov_b32 v[50:51], v[8:9], v[8:9]
	v_pk_mov_b32 v[52:53], v[8:9], v[8:9]
	v_pk_mov_b32 v[54:55], v[8:9], v[8:9]
	v_pk_mov_b32 v[56:57], v[8:9], v[8:9]
	v_pk_mov_b32 v[58:59], v[8:9], v[8:9]
	v_pk_mov_b32 v[60:61], v[8:9], v[8:9]
	v_pk_mov_b32 v[62:63], v[8:9], v[8:9]
	v_pk_mov_b32 v[64:65], v[8:9], v[8:9]
	v_pk_mov_b32 v[66:67], v[8:9], v[8:9]
	v_pk_mov_b32 v[68:69], v[8:9], v[8:9]
	v_pk_mov_b32 v[70:71], v[8:9], v[8:9]
	v_pk_mov_b32 v[72:73], v[8:9], v[8:9]
	v_pk_mov_b32 v[74:75], v[8:9], v[8:9]
	v_pk_mov_b32 v[76:77], v[8:9], v[8:9]
	v_pk_mov_b32 v[78:79], v[8:9], v[8:9]
	v_pk_mov_b32 v[80:81], v[8:9], v[8:9]
	v_pk_mov_b32 v[82:83], v[8:9], v[8:9]
	v_pk_mov_b32 v[84:85], v[8:9], v[8:9]
	v_pk_mov_b32 v[86:87], v[8:9], v[8:9]
	v_pk_mov_b32 v[88:89], v[8:9], v[8:9]
	v_pk_mov_b32 v[90:91], v[8:9], v[8:9]
	v_pk_mov_b32 v[92:93], v[8:9], v[8:9]
	v_pk_mov_b32 v[94:95], v[8:9], v[8:9]
	v_pk_mov_b32 v[96:97], v[8:9], v[8:9]
	v_pk_mov_b32 v[98:99], v[8:9], v[8:9]
	v_pk_mov_b32 v[100:101], v[8:9], v[8:9]
	v_pk_mov_b32 v[102:103], v[8:9], v[8:9]
	v_pk_mov_b32 v[104:105], v[8:9], v[8:9]
	v_pk_mov_b32 v[106:107], v[8:9], v[8:9]
	v_pk_mov_b32 v[108:109], v[8:9], v[8:9]
	v_pk_mov_b32 v[110:111], v[8:9], v[8:9]
	v_pk_mov_b32 v[112:113], v[8:9], v[8:9]
	v_pk_mov_b32 v[114:115], v[8:9], v[8:9]
	v_pk_mov_b32 v[116:117], v[8:9], v[8:9]
	v_pk_mov_b32 v[118:119], v[8:9], v[8:9]
	v_pk_mov_b32 v[120:121], v[8:9], v[8:9]
	v_pk_mov_b32 v[122:123], v[8:9], v[8:9]
	v_pk_mov_b32 v[124:125], v[8:9], v[8:9]
	v_pk_mov_b32 v[126:127], v[8:9], v[8:9]

; template <class Epi, class Sched, bool ALIGN_EPI = false, bool SP2 = false>
; __device__ __forceinline__ void gemm_phase(PG8_LAS unsigned char* lds, const Gemm g, const Sched& S, const Epi& E) {
;     ...
;         const char* nA = has_next ? (const char*)g.A + (size_t)nxt.pm * tstep : cA; const char* nB = has_next ? (const char*)g.Bt + (size_t)nxt.pn * tstep : cB;
;     ...
;         for (int a = 0; a < 2; ++a)
; #pragma unroll
;             for (int b = 0; b < 2; ++b)
; #pragma unroll
;                 for (int m = 0; m < 4; ++m)
; #pragma unroll
;                     for (int n = 0; n < 2; ++n) acc[a][b][m][n] = (f32x4){0.f, 0.f, 0.f, 0.f};
.LBB0_659:
	s_add_u32 s28, s10, 0xb0080
	s_addc_u32 s29, s11, 0
	s_add_u32 s57, s6, 0x100
	v_mov_b32_e32 v0, 0
	s_addc_u32 s58, s7, 0
	s_mov_b32 s59, -2
	s_waitcnt lgkmcnt(0)
	v_mov_b32_e32 v1, 0
	v_pk_mov_b32 v[2:3], v[0:1], v[0:1]
	v_pk_mov_b32 v[4:5], v[0:1], v[0:1]
	v_pk_mov_b32 v[6:7], v[0:1], v[0:1]
	v_pk_mov_b32 v[8:9], v[0:1], v[0:1]
	v_pk_mov_b32 v[10:11], v[0:1], v[0:1]
	v_pk_mov_b32 v[12:13], v[0:1], v[0:1]
	v_pk_mov_b32 v[14:15], v[0:1], v[0:1]
	v_pk_mov_b32 v[16:17], v[0:1], v[0:1]
	v_pk_mov_b32 v[18:19], v[0:1], v[0:1]
	v_pk_mov_b32 v[20:21], v[0:1], v[0:1]
	v_pk_mov_b32 v[22:23], v[0:1], v[0:1]
	v_pk_mov_b32 v[24:25], v[0:1], v[0:1]
	v_pk_mov_b32 v[26:27], v[0:1], v[0:1]
	v_pk_mov_b32 v[28:29], v[0:1], v[0:1]
	v_pk_mov_b32 v[30:31], v[0:1], v[0:1]
	v_pk_mov_b32 v[32:33], v[0:1], v[0:1]
	v_pk_mov_b32 v[34:35], v[0:1], v[0:1]
	v_pk_mov_b32 v[36:37], v[0:1], v[0:1]
	v_pk_mov_b32 v[38:39], v[0:1], v[0:1]
	v_pk_mov_b32 v[40:41], v[0:1], v[0:1]
	v_pk_mov_b32 v[42:43], v[0:1], v[0:1]
	v_pk_mov_b32 v[44:45], v[0:1], v[0:1]
	v_pk_mov_b32 v[46:47], v[0:1], v[0:1]
	v_pk_mov_b32 v[48:49], v[0:1], v[0:1]
	v_pk_mov_b32 v[50:51], v[0:1], v[0:1]
	v_pk_mov_b32 v[52:53], v[0:1], v[0:1]
	v_pk_mov_b32 v[54:55], v[0:1], v[0:1]
	v_pk_mov_b32 v[56:57], v[0:1], v[0:1]
	v_pk_mov_b32 v[58:59], v[0:1], v[0:1]
	v_pk_mov_b32 v[60:61], v[0:1], v[0:1]
	v_pk_mov_b32 v[62:63], v[0:1], v[0:1]
	v_pk_mov_b32 v[64:65], v[0:1], v[0:1]
	v_pk_mov_b32 v[66:67], v[0:1], v[0:1]
	v_pk_mov_b32 v[68:69], v[0:1], v[0:1]
	v_pk_mov_b32 v[70:71], v[0:1], v[0:1]
	v_pk_mov_b32 v[72:73], v[0:1], v[0:1]
	v_pk_mov_b32 v[74:75], v[0:1], v[0:1]
	v_pk_mov_b32 v[76:77], v[0:1], v[0:1]
	v_pk_mov_b32 v[78:79], v[0:1], v[0:1]
	v_pk_mov_b32 v[80:81], v[0:1], v[0:1]
	v_pk_mov_b32 v[82:83], v[0:1], v[0:1]
	v_pk_mov_b32 v[84:85], v[0:1], v[0:1]
	v_pk_mov_b32 v[86:87], v[0:1], v[0:1]
	v_pk_mov_b32 v[88:89], v[0:1], v[0:1]
	v_pk_mov_b32 v[90:91], v[0:1], v[0:1]
	v_pk_mov_b32 v[92:93], v[0:1], v[0:1]
	v_pk_mov_b32 v[94:95], v[0:1], v[0:1]
	v_pk_mov_b32 v[96:97], v[0:1], v[0:1]
	v_pk_mov_b32 v[98:99], v[0:1], v[0:1]
	v_pk_mov_b32 v[100:101], v[0:1], v[0:1]
	v_pk_mov_b32 v[102:103], v[0:1], v[0:1]
	v_pk_mov_b32 v[104:105], v[0:1], v[0:1]
	v_pk_mov_b32 v[106:107], v[0:1], v[0:1]
	v_pk_mov_b32 v[108:109], v[0:1], v[0:1]
	v_pk_mov_b32 v[110:111], v[0:1], v[0:1]
	v_pk_mov_b32 v[112:113], v[0:1], v[0:1]
	v_pk_mov_b32 v[114:115], v[0:1], v[0:1]
	v_pk_mov_b32 v[116:117], v[0:1], v[0:1]
	v_pk_mov_b32 v[118:119], v[0:1], v[0:1]
	v_pk_mov_b32 v[120:121], v[0:1], v[0:1]
	v_pk_mov_b32 v[122:123], v[0:1], v[0:1]
	v_pk_mov_b32 v[124:125], v[0:1], v[0:1]
	v_pk_mov_b32 v[126:127], v[0:1], v[0:1]

; template <class Epi, class Sched, bool ALIGN_EPI = false, bool SP2 = false>
; __device__ __forceinline__ void gemm_phase(PG8_LAS unsigned char* lds, const Gemm g, const Sched& S, const Epi& E) {
;     ...
;         const bool has_next = S.next(ui + 1, nxt);
;         const char* nA = has_next ? (const char*)g.A + (size_t)nxt.pm * tstep : cA; const char* nB = has_next ? (const char*)g.Bt + (size_t)nxt.pn * tstep : cB;
;     ...
;         for (int a = 0; a < 2; ++a)
; #pragma unroll
;             for (int b = 0; b < 2; ++b)
; #pragma unroll
;                 for (int m = 0; m < 4; ++m)
; #pragma unroll
;                     for (int n = 0; n < 2; ++n) acc[a][b][m][n] = (f32x4){0.f, 0.f, 0.f, 0.f};
.LBB0_813:
	s_ashr_i32 s27, s26, 31
	s_lshl_b64 s[28:29], s[26:27], 19
	s_add_u32 s28, s38, s28
	s_addc_u32 s29, s39, s29
	s_and_b64 s[30:31], s[0:1], exec
	s_cselect_b32 s27, s29, s11
	s_cselect_b32 s58, s28, s10
	s_ashr_i32 s21, s20, 31
	s_lshl_b64 s[30:31], s[20:21], 19
	v_readlane_b32 s36, v248, 10
	v_readlane_b32 s37, v248, 11
	s_add_u32 s30, s36, s30
	s_addc_u32 s31, s37, s31
	s_and_b64 s[36:37], s[0:1], exec
	s_cselect_b32 s21, s31, s7
	s_cselect_b32 s59, s30, s6
	s_add_u32 s36, s10, 0x40080
	s_addc_u32 s37, s11, 0
	s_add_u32 s60, s6, 0x100
	v_mov_b32_e32 v0, 0
	s_addc_u32 s61, s7, 0
	s_mov_b32 s62, -2
	v_mov_b32_e32 v1, 0
	v_pk_mov_b32 v[2:3], v[0:1], v[0:1]
	v_pk_mov_b32 v[4:5], v[0:1], v[0:1]
	v_pk_mov_b32 v[6:7], v[0:1], v[0:1]
	v_pk_mov_b32 v[8:9], v[0:1], v[0:1]
	v_pk_mov_b32 v[10:11], v[0:1], v[0:1]
	v_pk_mov_b32 v[12:13], v[0:1], v[0:1]
	v_pk_mov_b32 v[14:15], v[0:1], v[0:1]
	v_pk_mov_b32 v[16:17], v[0:1], v[0:1]
	v_pk_mov_b32 v[18:19], v[0:1], v[0:1]
	v_pk_mov_b32 v[20:21], v[0:1], v[0:1]
	v_pk_mov_b32 v[22:23], v[0:1], v[0:1]
	v_pk_mov_b32 v[24:25], v[0:1], v[0:1]
	v_pk_mov_b32 v[26:27], v[0:1], v[0:1]
	v_pk_mov_b32 v[28:29], v[0:1], v[0:1]
	v_pk_mov_b32 v[30:31], v[0:1], v[0:1]
	v_pk_mov_b32 v[32:33], v[0:1], v[0:1]
	v_pk_mov_b32 v[34:35], v[0:1], v[0:1]
	v_pk_mov_b32 v[36:37], v[0:1], v[0:1]
	v_pk_mov_b32 v[38:39], v[0:1], v[0:1]
	v_pk_mov_b32 v[40:41], v[0:1], v[0:1]
	v_pk_mov_b32 v[42:43], v[0:1], v[0:1]
	v_pk_mov_b32 v[44:45], v[0:1], v[0:1]
	v_pk_mov_b32 v[46:47], v[0:1], v[0:1]
	v_pk_mov_b32 v[48:49], v[0:1], v[0:1]
	v_pk_mov_b32 v[50:51], v[0:1], v[0:1]
	v_pk_mov_b32 v[52:53], v[0:1], v[0:1]
	v_pk_mov_b32 v[54:55], v[0:1], v[0:1]
	v_pk_mov_b32 v[56:57], v[0:1], v[0:1]
	v_pk_mov_b32 v[58:59], v[0:1], v[0:1]
	v_pk_mov_b32 v[60:61], v[0:1], v[0:1]
	v_pk_mov_b32 v[62:63], v[0:1], v[0:1]
	v_pk_mov_b32 v[64:65], v[0:1], v[0:1]
	v_pk_mov_b32 v[66:67], v[0:1], v[0:1]
	v_pk_mov_b32 v[68:69], v[0:1], v[0:1]
	v_pk_mov_b32 v[70:71], v[0:1], v[0:1]
	v_pk_mov_b32 v[72:73], v[0:1], v[0:1]
	v_pk_mov_b32 v[74:75], v[0:1], v[0:1]
	v_pk_mov_b32 v[76:77], v[0:1], v[0:1]
	v_pk_mov_b32 v[78:79], v[0:1], v[0:1]
	v_pk_mov_b32 v[80:81], v[0:1], v[0:1]
	v_pk_mov_b32 v[82:83], v[0:1], v[0:1]
	v_pk_mov_b32 v[84:85], v[0:1], v[0:1]
	v_pk_mov_b32 v[86:87], v[0:1], v[0:1]
	v_pk_mov_b32 v[88:89], v[0:1], v[0:1]
	v_pk_mov_b32 v[90:91], v[0:1], v[0:1]
	v_pk_mov_b32 v[92:93], v[0:1], v[0:1]
	v_pk_mov_b32 v[94:95], v[0:1], v[0:1]
	v_pk_mov_b32 v[96:97], v[0:1], v[0:1]
	v_pk_mov_b32 v[98:99], v[0:1], v[0:1]
	v_pk_mov_b32 v[100:101], v[0:1], v[0:1]
	v_pk_mov_b32 v[102:103], v[0:1], v[0:1]
	v_pk_mov_b32 v[104:105], v[0:1], v[0:1]
	v_pk_mov_b32 v[106:107], v[0:1], v[0:1]
	v_pk_mov_b32 v[108:109], v[0:1], v[0:1]
	v_pk_mov_b32 v[110:111], v[0:1], v[0:1]
	v_pk_mov_b32 v[112:113], v[0:1], v[0:1]
	v_pk_mov_b32 v[114:115], v[0:1], v[0:1]
	v_pk_mov_b32 v[116:117], v[0:1], v[0:1]
	v_pk_mov_b32 v[118:119], v[0:1], v[0:1]
	v_pk_mov_b32 v[120:121], v[0:1], v[0:1]
	v_pk_mov_b32 v[122:123], v[0:1], v[0:1]
	v_pk_mov_b32 v[124:125], v[0:1], v[0:1]
	v_pk_mov_b32 v[126:127], v[0:1], v[0:1]

; template <class Epi, class Sched, bool ALIGN_EPI = false, bool SP2 = false>
; __device__ __forceinline__ void gemm_phase(PG8_LAS unsigned char* lds, const Gemm g, const Sched& S, const Epi& E) {
;     ...
;         const bool has_next = S.next(ui + 1, nxt);
;         const char* nA = has_next ? (const char*)g.A + (size_t)nxt.pm * tstep : cA; const char* nB = has_next ? (const char*)g.Bt + (size_t)nxt.pn * tstep : cB;
;     ...
;         for (int a = 0; a < 2; ++a)
; #pragma unroll
;             for (int b = 0; b < 2; ++b)
; #pragma unroll
;                 for (int m = 0; m < 4; ++m)
; #pragma unroll
;                     for (int n = 0; n < 2; ++n) acc[a][b][m][n] = (f32x4){0.f, 0.f, 0.f, 0.f};
.LBB0_837:
	s_ashr_i32 s21, s20, 31
	s_lshl_b64 s[22:23], s[20:21], 19
	s_add_u32 s22, s33, s22
	s_addc_u32 s23, s36, s23
	s_and_b64 s[26:27], s[0:1], exec
	s_cselect_b32 s21, s23, s31
	s_cselect_b32 s61, s22, s30
	s_ashr_i32 s19, s18, 31
	s_lshl_b64 s[26:27], s[18:19], 19
	s_add_u32 s26, s38, s26
	s_addc_u32 s27, s39, s27
	s_and_b64 s[34:35], s[0:1], exec
	s_cselect_b32 s19, s27, s7
	s_cselect_b32 s62, s26, s6
	s_add_u32 s30, s30, 0x40080
	s_addc_u32 s31, s31, 0
	s_add_u32 s63, s6, 0x100
	v_mov_b32_e32 v0, 0
	s_addc_u32 s64, s7, 0
	s_mov_b32 s65, -2
	v_mov_b32_e32 v1, 0
	v_pk_mov_b32 v[2:3], v[0:1], v[0:1]
	v_pk_mov_b32 v[4:5], v[0:1], v[0:1]
	v_pk_mov_b32 v[6:7], v[0:1], v[0:1]
	v_pk_mov_b32 v[8:9], v[0:1], v[0:1]
	v_pk_mov_b32 v[10:11], v[0:1], v[0:1]
	v_pk_mov_b32 v[12:13], v[0:1], v[0:1]
	v_pk_mov_b32 v[14:15], v[0:1], v[0:1]
	v_pk_mov_b32 v[16:17], v[0:1], v[0:1]
	v_pk_mov_b32 v[18:19], v[0:1], v[0:1]
	v_pk_mov_b32 v[20:21], v[0:1], v[0:1]
	v_pk_mov_b32 v[22:23], v[0:1], v[0:1]
	v_pk_mov_b32 v[24:25], v[0:1], v[0:1]
	v_pk_mov_b32 v[26:27], v[0:1], v[0:1]
	v_pk_mov_b32 v[28:29], v[0:1], v[0:1]
	v_pk_mov_b32 v[30:31], v[0:1], v[0:1]
	v_pk_mov_b32 v[32:33], v[0:1], v[0:1]
	v_pk_mov_b32 v[34:35], v[0:1], v[0:1]
	v_pk_mov_b32 v[36:37], v[0:1], v[0:1]
	v_pk_mov_b32 v[38:39], v[0:1], v[0:1]
	v_pk_mov_b32 v[40:41], v[0:1], v[0:1]
	v_pk_mov_b32 v[42:43], v[0:1], v[0:1]
	v_pk_mov_b32 v[44:45], v[0:1], v[0:1]
	v_pk_mov_b32 v[46:47], v[0:1], v[0:1]
	v_pk_mov_b32 v[48:49], v[0:1], v[0:1]
	v_pk_mov_b32 v[50:51], v[0:1], v[0:1]
	v_pk_mov_b32 v[52:53], v[0:1], v[0:1]
	v_pk_mov_b32 v[54:55], v[0:1], v[0:1]
	v_pk_mov_b32 v[56:57], v[0:1], v[0:1]
	v_pk_mov_b32 v[58:59], v[0:1], v[0:1]
	v_pk_mov_b32 v[60:61], v[0:1], v[0:1]
	v_pk_mov_b32 v[62:63], v[0:1], v[0:1]
	v_pk_mov_b32 v[64:65], v[0:1], v[0:1]
	v_pk_mov_b32 v[66:67], v[0:1], v[0:1]
	v_pk_mov_b32 v[68:69], v[0:1], v[0:1]
	v_pk_mov_b32 v[70:71], v[0:1], v[0:1]
	v_pk_mov_b32 v[72:73], v[0:1], v[0:1]
	v_pk_mov_b32 v[74:75], v[0:1], v[0:1]
	v_pk_mov_b32 v[76:77], v[0:1], v[0:1]
	v_pk_mov_b32 v[78:79], v[0:1], v[0:1]
	v_pk_mov_b32 v[80:81], v[0:1], v[0:1]
	v_pk_mov_b32 v[82:83], v[0:1], v[0:1]
	v_pk_mov_b32 v[84:85], v[0:1], v[0:1]
	v_pk_mov_b32 v[86:87], v[0:1], v[0:1]
	v_pk_mov_b32 v[88:89], v[0:1], v[0:1]
	v_pk_mov_b32 v[90:91], v[0:1], v[0:1]
	v_pk_mov_b32 v[92:93], v[0:1], v[0:1]
	v_pk_mov_b32 v[94:95], v[0:1], v[0:1]
	v_pk_mov_b32 v[96:97], v[0:1], v[0:1]
	v_pk_mov_b32 v[98:99], v[0:1], v[0:1]
	v_pk_mov_b32 v[100:101], v[0:1], v[0:1]
	v_pk_mov_b32 v[102:103], v[0:1], v[0:1]
	v_pk_mov_b32 v[104:105], v[0:1], v[0:1]
	v_pk_mov_b32 v[106:107], v[0:1], v[0:1]
	v_pk_mov_b32 v[108:109], v[0:1], v[0:1]
	v_pk_mov_b32 v[110:111], v[0:1], v[0:1]
	v_pk_mov_b32 v[112:113], v[0:1], v[0:1]
	v_pk_mov_b32 v[114:115], v[0:1], v[0:1]
	v_pk_mov_b32 v[116:117], v[0:1], v[0:1]
	v_pk_mov_b32 v[118:119], v[0:1], v[0:1]
	v_pk_mov_b32 v[120:121], v[0:1], v[0:1]
	v_pk_mov_b32 v[122:123], v[0:1], v[0:1]
	v_pk_mov_b32 v[124:125], v[0:1], v[0:1]
	v_pk_mov_b32 v[126:127], v[0:1], v[0:1]

; template <class Epi, class Sched, bool ALIGN_EPI = false, bool SP2 = false>
; __device__ __forceinline__ void gemm_phase(PG8_LAS unsigned char* lds, const Gemm g, const Sched& S, const Epi& E) {
;     ...
;         const bool has_next = S.next(ui + 1, nxt);
;         const char* nA = has_next ? (const char*)g.A + (size_t)nxt.pm * tstep : cA; const char* nB = has_next ? (const char*)g.Bt + (size_t)nxt.pn * tstep : cB;
;     ...
;         for (int a = 0; a < 2; ++a)
; #pragma unroll
;             for (int b = 0; b < 2; ++b)
; #pragma unroll
;                 for (int m = 0; m < 4; ++m)
; #pragma unroll
;                     for (int n = 0; n < 2; ++n) acc[a][b][m][n] = (f32x4){0.f, 0.f, 0.f, 0.f};
.LBB0_986:
	s_ashr_i32 s25, s24, 31
	s_lshl_b64 s[26:27], s[24:25], 19
	s_add_u32 s26, s44, s26
	s_addc_u32 s27, s45, s27
	s_and_b64 s[28:29], s[4:5], exec
	s_cselect_b32 s25, s27, s9
	s_cselect_b32 s55, s26, s8
	s_ashr_i32 s23, s22, 31
	s_lshl_b64 s[28:29], s[22:23], 19
	v_readlane_b32 s34, v248, 12
	v_readlane_b32 s35, v248, 13
	s_add_u32 s28, s34, s28
	s_addc_u32 s29, s35, s29
	s_and_b64 s[34:35], s[4:5], exec
	s_cselect_b32 s23, s29, s7
	s_cselect_b32 s56, s28, s6
	s_add_u32 s8, s8, 0x40080
	s_addc_u32 s9, s9, 0
	s_add_u32 s57, s6, 0x100
	v_mov_b32_e32 v0, 0
	s_addc_u32 s58, s7, 0
	s_mov_b32 s59, -2
	s_waitcnt lgkmcnt(0)
	v_mov_b32_e32 v1, 0
	v_pk_mov_b32 v[2:3], v[0:1], v[0:1]
	v_pk_mov_b32 v[4:5], v[0:1], v[0:1]
	v_pk_mov_b32 v[6:7], v[0:1], v[0:1]
	v_pk_mov_b32 v[8:9], v[0:1], v[0:1]
	v_pk_mov_b32 v[10:11], v[0:1], v[0:1]
	v_pk_mov_b32 v[12:13], v[0:1], v[0:1]
	v_pk_mov_b32 v[14:15], v[0:1], v[0:1]
	v_pk_mov_b32 v[16:17], v[0:1], v[0:1]
	v_pk_mov_b32 v[18:19], v[0:1], v[0:1]
	v_pk_mov_b32 v[20:21], v[0:1], v[0:1]
	v_pk_mov_b32 v[22:23], v[0:1], v[0:1]
	v_pk_mov_b32 v[24:25], v[0:1], v[0:1]
	v_pk_mov_b32 v[26:27], v[0:1], v[0:1]
	v_pk_mov_b32 v[28:29], v[0:1], v[0:1]
	v_pk_mov_b32 v[30:31], v[0:1], v[0:1]
	v_pk_mov_b32 v[32:33], v[0:1], v[0:1]
	v_pk_mov_b32 v[34:35], v[0:1], v[0:1]
	v_pk_mov_b32 v[36:37], v[0:1], v[0:1]
	v_pk_mov_b32 v[38:39], v[0:1], v[0:1]
	v_pk_mov_b32 v[40:41], v[0:1], v[0:1]
	v_pk_mov_b32 v[42:43], v[0:1], v[0:1]
	v_pk_mov_b32 v[44:45], v[0:1], v[0:1]
	v_pk_mov_b32 v[46:47], v[0:1], v[0:1]
	v_pk_mov_b32 v[48:49], v[0:1], v[0:1]
	v_pk_mov_b32 v[50:51], v[0:1], v[0:1]
	v_pk_mov_b32 v[52:53], v[0:1], v[0:1]
	v_pk_mov_b32 v[54:55], v[0:1], v[0:1]
	v_pk_mov_b32 v[56:57], v[0:1], v[0:1]
	v_pk_mov_b32 v[58:59], v[0:1], v[0:1]
	v_pk_mov_b32 v[60:61], v[0:1], v[0:1]
	v_pk_mov_b32 v[62:63], v[0:1], v[0:1]
	v_pk_mov_b32 v[64:65], v[0:1], v[0:1]
	v_pk_mov_b32 v[66:67], v[0:1], v[0:1]
	v_pk_mov_b32 v[68:69], v[0:1], v[0:1]
	v_pk_mov_b32 v[70:71], v[0:1], v[0:1]
	v_pk_mov_b32 v[72:73], v[0:1], v[0:1]
	v_pk_mov_b32 v[74:75], v[0:1], v[0:1]
	v_pk_mov_b32 v[76:77], v[0:1], v[0:1]
	v_pk_mov_b32 v[78:79], v[0:1], v[0:1]
	v_pk_mov_b32 v[88:89], v[0:1], v[0:1]
	v_pk_mov_b32 v[90:91], v[0:1], v[0:1]
	v_pk_mov_b32 v[100:101], v[0:1], v[0:1]
	v_pk_mov_b32 v[102:103], v[0:1], v[0:1]
	v_pk_mov_b32 v[104:105], v[0:1], v[0:1]
	v_pk_mov_b32 v[106:107], v[0:1], v[0:1]
	v_pk_mov_b32 v[108:109], v[0:1], v[0:1]
	v_pk_mov_b32 v[110:111], v[0:1], v[0:1]
	v_pk_mov_b32 v[112:113], v[0:1], v[0:1]
	v_pk_mov_b32 v[114:115], v[0:1], v[0:1]
	v_pk_mov_b32 v[116:117], v[0:1], v[0:1]
	v_pk_mov_b32 v[118:119], v[0:1], v[0:1]
	v_pk_mov_b32 v[120:121], v[0:1], v[0:1]
	v_pk_mov_b32 v[122:123], v[0:1], v[0:1]
	v_pk_mov_b32 v[124:125], v[0:1], v[0:1]
	v_pk_mov_b32 v[126:127], v[0:1], v[0:1]
	v_pk_mov_b32 v[128:129], v[0:1], v[0:1]
	v_pk_mov_b32 v[130:131], v[0:1], v[0:1]
	v_pk_mov_b32 v[132:133], v[0:1], v[0:1]
	v_pk_mov_b32 v[134:135], v[0:1], v[0:1]
	v_pk_mov_b32 v[136:137], v[0:1], v[0:1]
	v_pk_mov_b32 v[138:139], v[0:1], v[0:1]
	v_pk_mov_b32 v[140:141], v[0:1], v[0:1]
	v_pk_mov_b32 v[142:143], v[0:1], v[0:1]

; template <class Epi, class Sched, bool ALIGN_EPI = false, bool SP2 = false>
; __device__ __forceinline__ void gemm_phase(PG8_LAS unsigned char* lds, const Gemm g, const Sched& S, const Epi& E) {
;     ...
;         const bool has_next = S.next(ui + 1, nxt);
;         const char* nA = has_next ? (const char*)g.A + (size_t)nxt.pm * tstep : cA; const char* nB = has_next ? (const char*)g.Bt + (size_t)nxt.pn * tstep : cB;
;     ...
;         for (int a = 0; a < 2; ++a)
; #pragma unroll
;             for (int b = 0; b < 2; ++b)
; #pragma unroll
;                 for (int m = 0; m < 4; ++m)
; #pragma unroll
;                     for (int n = 0; n < 2; ++n) acc[a][b][m][n] = (f32x4){0.f, 0.f, 0.f, 0.f};
.LBB0_1081:
	s_ashr_i32 s17, s16, 31
	s_lshl_b64 s[18:19], s[16:17], 19
	s_add_u32 s18, s38, s18
	s_addc_u32 s19, s39, s19
	s_and_b64 s[20:21], s[0:1], exec
	s_cselect_b32 s17, s19, s25
	s_cselect_b32 s51, s18, s24
	s_ashr_i32 s15, s14, 31
	s_lshl_b64 s[20:21], s[14:15], 19
	s_add_u32 s20, s3, s20
	s_addc_u32 s21, s28, s21
	s_and_b64 s[26:27], s[0:1], exec
	s_cselect_b32 s15, s21, s7
	s_cselect_b32 s52, s20, s6
	s_add_u32 s24, s24, 0x40080
	s_addc_u32 s25, s25, 0
	s_add_u32 s53, s6, 0x100
	v_mov_b32_e32 v8, 0
	s_addc_u32 s54, s7, 0
	s_mov_b32 s55, -2
	v_mov_b32_e32 v9, 0
	v_pk_mov_b32 v[0:1], v[8:9], v[8:9]
	v_pk_mov_b32 v[2:3], v[8:9], v[8:9]
	v_pk_mov_b32 v[4:5], v[8:9], v[8:9]
	v_pk_mov_b32 v[6:7], v[8:9], v[8:9]
	v_pk_mov_b32 v[10:11], v[8:9], v[8:9]
	v_pk_mov_b32 v[12:13], v[8:9], v[8:9]
	v_pk_mov_b32 v[14:15], v[8:9], v[8:9]
	v_pk_mov_b32 v[16:17], v[8:9], v[8:9]
	v_pk_mov_b32 v[18:19], v[8:9], v[8:9]
	v_pk_mov_b32 v[20:21], v[8:9], v[8:9]
	v_pk_mov_b32 v[22:23], v[8:9], v[8:9]
	v_pk_mov_b32 v[24:25], v[8:9], v[8:9]
	v_pk_mov_b32 v[26:27], v[8:9], v[8:9]
	v_pk_mov_b32 v[28:29], v[8:9], v[8:9]
	v_pk_mov_b32 v[30:31], v[8:9], v[8:9]
	v_pk_mov_b32 v[32:33], v[8:9], v[8:9]
	v_pk_mov_b32 v[34:35], v[8:9], v[8:9]
	v_pk_mov_b32 v[36:37], v[8:9], v[8:9]
	v_pk_mov_b32 v[38:39], v[8:9], v[8:9]
	v_pk_mov_b32 v[40:41], v[8:9], v[8:9]
	v_pk_mov_b32 v[42:43], v[8:9], v[8:9]
	v_pk_mov_b32 v[44:45], v[8:9], v[8:9]
	v_pk_mov_b32 v[46:47], v[8:9], v[8:9]
	v_pk_mov_b32 v[48:49], v[8:9], v[8:9]
	v_pk_mov_b32 v[50:51], v[8:9], v[8:9]
	v_pk_mov_b32 v[52:53], v[8:9], v[8:9]
	v_pk_mov_b32 v[54:55], v[8:9], v[8:9]
	v_pk_mov_b32 v[56:57], v[8:9], v[8:9]
	v_pk_mov_b32 v[58:59], v[8:9], v[8:9]
	v_pk_mov_b32 v[60:61], v[8:9], v[8:9]
	v_pk_mov_b32 v[62:63], v[8:9], v[8:9]
	v_pk_mov_b32 v[64:65], v[8:9], v[8:9]
	v_pk_mov_b32 v[66:67], v[8:9], v[8:9]
	v_pk_mov_b32 v[68:69], v[8:9], v[8:9]
	v_pk_mov_b32 v[70:71], v[8:9], v[8:9]
	v_pk_mov_b32 v[72:73], v[8:9], v[8:9]
	v_pk_mov_b32 v[74:75], v[8:9], v[8:9]
	v_pk_mov_b32 v[76:77], v[8:9], v[8:9]
	v_pk_mov_b32 v[78:79], v[8:9], v[8:9]
	v_pk_mov_b32 v[80:81], v[8:9], v[8:9]
	v_pk_mov_b32 v[82:83], v[8:9], v[8:9]
	v_pk_mov_b32 v[84:85], v[8:9], v[8:9]
	v_pk_mov_b32 v[86:87], v[8:9], v[8:9]
	v_pk_mov_b32 v[88:89], v[8:9], v[8:9]
	v_pk_mov_b32 v[90:91], v[8:9], v[8:9]
	v_pk_mov_b32 v[92:93], v[8:9], v[8:9]
	v_pk_mov_b32 v[94:95], v[8:9], v[8:9]
	v_pk_mov_b32 v[96:97], v[8:9], v[8:9]
	v_pk_mov_b32 v[98:99], v[8:9], v[8:9]
	v_pk_mov_b32 v[100:101], v[8:9], v[8:9]
	v_pk_mov_b32 v[102:103], v[8:9], v[8:9]
	v_pk_mov_b32 v[104:105], v[8:9], v[8:9]
	v_pk_mov_b32 v[106:107], v[8:9], v[8:9]
	v_pk_mov_b32 v[108:109], v[8:9], v[8:9]
	v_pk_mov_b32 v[110:111], v[8:9], v[8:9]
	v_pk_mov_b32 v[112:113], v[8:9], v[8:9]
	v_pk_mov_b32 v[114:115], v[8:9], v[8:9]
	v_pk_mov_b32 v[116:117], v[8:9], v[8:9]
	v_pk_mov_b32 v[118:119], v[8:9], v[8:9]
	v_pk_mov_b32 v[120:121], v[8:9], v[8:9]
	v_pk_mov_b32 v[122:123], v[8:9], v[8:9]
	v_pk_mov_b32 v[124:125], v[8:9], v[8:9]
	v_pk_mov_b32 v[126:127], v[8:9], v[8:9]

; template <class Epi, class Sched, bool ALIGN_EPI = false, bool SP2 = false>
; __device__ __forceinline__ void gemm_phase(PG8_LAS unsigned char* lds, const Gemm g, const Sched& S, const Epi& E) {
;     ...
;         const char* nA = has_next ? (const char*)g.A + (size_t)nxt.pm * tstep : cA; const char* nB = has_next ? (const char*)g.Bt + (size_t)nxt.pn * tstep : cB;
;     ...
;         for (int a = 0; a < 2; ++a)
; #pragma unroll
;             for (int b = 0; b < 2; ++b)
; #pragma unroll
;                 for (int m = 0; m < 4; ++m)
; #pragma unroll
;                     for (int n = 0; n < 2; ++n) acc[a][b][m][n] = (f32x4){0.f, 0.f, 0.f, 0.f};
.LBB0_1166:
	s_add_u32 s22, s22, 0xb0080
	s_addc_u32 s23, s23, 0
	s_add_u32 s51, s6, 0x100
	v_mov_b32_e32 v0, 0
	s_addc_u32 s52, s7, 0
	s_mov_b32 s53, -2
	s_waitcnt lgkmcnt(0)
	v_mov_b32_e32 v1, 0
	v_pk_mov_b32 v[2:3], v[0:1], v[0:1]
	v_pk_mov_b32 v[4:5], v[0:1], v[0:1]
	v_pk_mov_b32 v[6:7], v[0:1], v[0:1]
	v_pk_mov_b32 v[8:9], v[0:1], v[0:1]
	v_pk_mov_b32 v[10:11], v[0:1], v[0:1]
	v_pk_mov_b32 v[12:13], v[0:1], v[0:1]
	v_pk_mov_b32 v[14:15], v[0:1], v[0:1]
	v_pk_mov_b32 v[16:17], v[0:1], v[0:1]
	v_pk_mov_b32 v[18:19], v[0:1], v[0:1]
	v_pk_mov_b32 v[20:21], v[0:1], v[0:1]
	v_pk_mov_b32 v[22:23], v[0:1], v[0:1]
	v_pk_mov_b32 v[24:25], v[0:1], v[0:1]
	v_pk_mov_b32 v[26:27], v[0:1], v[0:1]
	v_pk_mov_b32 v[28:29], v[0:1], v[0:1]
	v_pk_mov_b32 v[30:31], v[0:1], v[0:1]
	v_pk_mov_b32 v[32:33], v[0:1], v[0:1]
	v_pk_mov_b32 v[34:35], v[0:1], v[0:1]
	v_pk_mov_b32 v[36:37], v[0:1], v[0:1]
	v_pk_mov_b32 v[38:39], v[0:1], v[0:1]
	v_pk_mov_b32 v[40:41], v[0:1], v[0:1]
	v_pk_mov_b32 v[42:43], v[0:1], v[0:1]
	v_pk_mov_b32 v[44:45], v[0:1], v[0:1]
	v_pk_mov_b32 v[46:47], v[0:1], v[0:1]
	v_pk_mov_b32 v[48:49], v[0:1], v[0:1]
	v_pk_mov_b32 v[50:51], v[0:1], v[0:1]
	v_pk_mov_b32 v[52:53], v[0:1], v[0:1]
	v_pk_mov_b32 v[54:55], v[0:1], v[0:1]
	v_pk_mov_b32 v[56:57], v[0:1], v[0:1]
	v_pk_mov_b32 v[58:59], v[0:1], v[0:1]
	v_pk_mov_b32 v[60:61], v[0:1], v[0:1]
	v_pk_mov_b32 v[62:63], v[0:1], v[0:1]
	v_pk_mov_b32 v[64:65], v[0:1], v[0:1]
	v_pk_mov_b32 v[66:67], v[0:1], v[0:1]
	v_pk_mov_b32 v[68:69], v[0:1], v[0:1]
	v_pk_mov_b32 v[70:71], v[0:1], v[0:1]
	v_pk_mov_b32 v[72:73], v[0:1], v[0:1]
	v_pk_mov_b32 v[74:75], v[0:1], v[0:1]
	v_pk_mov_b32 v[76:77], v[0:1], v[0:1]
	v_pk_mov_b32 v[78:79], v[0:1], v[0:1]
	v_pk_mov_b32 v[80:81], v[0:1], v[0:1]
	v_pk_mov_b32 v[82:83], v[0:1], v[0:1]
	v_pk_mov_b32 v[84:85], v[0:1], v[0:1]
	v_pk_mov_b32 v[86:87], v[0:1], v[0:1]
	v_pk_mov_b32 v[88:89], v[0:1], v[0:1]
	v_pk_mov_b32 v[90:91], v[0:1], v[0:1]
	v_pk_mov_b32 v[92:93], v[0:1], v[0:1]
	v_pk_mov_b32 v[94:95], v[0:1], v[0:1]
	v_pk_mov_b32 v[96:97], v[0:1], v[0:1]
	v_pk_mov_b32 v[98:99], v[0:1], v[0:1]
	v_pk_mov_b32 v[100:101], v[0:1], v[0:1]
	v_pk_mov_b32 v[102:103], v[0:1], v[0:1]
	v_pk_mov_b32 v[104:105], v[0:1], v[0:1]
	v_pk_mov_b32 v[106:107], v[0:1], v[0:1]
	v_pk_mov_b32 v[108:109], v[0:1], v[0:1]
	v_pk_mov_b32 v[110:111], v[0:1], v[0:1]
	v_pk_mov_b32 v[112:113], v[0:1], v[0:1]
	v_pk_mov_b32 v[114:115], v[0:1], v[0:1]
	v_pk_mov_b32 v[116:117], v[0:1], v[0:1]
	v_pk_mov_b32 v[118:119], v[0:1], v[0:1]
	v_pk_mov_b32 v[120:121], v[0:1], v[0:1]
	v_pk_mov_b32 v[122:123], v[0:1], v[0:1]
	v_pk_mov_b32 v[124:125], v[0:1], v[0:1]
	v_pk_mov_b32 v[126:127], v[0:1], v[0:1]
